# v18 + warm-up loads of the row-statistics lines at the start of the in-projection and gate/up GEMM epilogues (serialized rstd loads then hit L1)
# speedup vs baseline: 1.0046x; 1.0046x over previous
; __device__ __forceinline__ void load_rstd8(const float* ssq, const float* ssqc, int row0, int fq, float (&rs)[2][4]) {
;     const bool isc = row0 >= ML;
; #pragma unroll
;     for (int ai = 0; ai < 2; ++ai)
; #pragma unroll
;         for (int m = 0; m < 4; ++m) {
;             const int row = row0 + ai * HALF + m * 16;
;             float s;
;             if (!isc) { const f32x4 a = *(const f32x4*)(ssq + ((size_t)(2 * fq) * MT + row) * 4), b = *(const f32x4*)(ssq + ((size_t)(2 * fq + 1) * MT + row) * 4);
;                 s = ((a[0] + a[1]) + (a[2] + a[3])) + ((b[0] + b[1]) + (b[2] + b[3])); }
;     __device__ __forceinline__ void operator()(const f32x4 (&acc)[2][2][4][2], const Unit& u, int wr, int wc, int fr_, int fq_) const {
;         int fr = fr_, fq = fq_; asm volatile("" : "+v"(fr), "+v"(fq));
;         const int row0 = u.pm * BM + wr * 64 + fr, v = vec_of_panel(u.pm);
;         const int pn = u.pn + pn_off;
;         float rs[2][4]; load_rstd8(ssq, ssqc, row0, fq, rs);
.LBB0_272:
	v_mov_b32_e32 v240, v189
	v_mov_b32_e32 v150, v191
	s_lshl_b32 s26, s88, 8
	s_add_i32 s26, s26, s71
	v_lshrrev_b32_e32 v246, 3, v201
	v_mul_u32_u24_e32 v246, 0x22000, v246
	v_and_b32_e32 v247, 3, v201
	v_bfe_u32 v248, v201, 2, 1
	v_lshlrev_b32_e32 v247, 6, v247
	v_lshl_add_u32 v247, v248, 8, v247
	s_lshl_b32 s74, s26, 4
	v_add3_u32 v246, v246, v247, s74
	global_load_dword v247, v246, s[46:47]
	global_load_dword v248, v246, s[46:47] offset:512
	global_load_dword v249, v246, s[46:47] offset:2048
	global_load_dword v250, v246, s[46:47] offset:2560
	v_lshlrev_b32_e32 v0, 1, v150
	v_add_u32_e32 v168, s26, v240
	v_mad_i64_i32 v[146:147], s[72:73], v0, s97, 0
	v_or_b32_e32 v0, 1, v0
	v_cmp_gt_i32_e64 s[40:41], s58, v168
	v_mad_i64_i32 v[148:149], s[72:73], v0, s97, 0
	v_ashrrev_i32_e32 v169, 31, v168
	s_and_saveexec_b64 s[72:73], s[40:41]
	s_xor_b64 s[90:91], exec, s[72:73]
	s_cbranch_execz .LBB0_274
	v_lshl_add_u64 v[130:131], v[146:147], 0, v[168:169]
	v_lshl_add_u64 v[132:133], v[148:149], 0, v[168:169]
	v_lshl_add_u64 v[130:131], v[130:131], 4, s[46:47]
	v_lshl_add_u64 v[134:135], v[132:133], 4, s[46:47]
	global_load_dwordx4 v[130:133], v[130:131], off
	s_nop 0
	global_load_dwordx4 v[134:137], v[134:135], off
	s_waitcnt vmcnt(0)
	v_mov_b32_e32 v138, v130
	v_mov_b32_e32 v139, v134
	v_mov_b32_e32 v134, v131
	v_mov_b32_e32 v130, v132
	v_mov_b32_e32 v131, v136
	v_mov_b32_e32 v136, v133
	v_pk_add_f32 v[132:133], v[138:139], v[134:135]
	v_pk_add_f32 v[130:131], v[130:131], v[136:137]
	s_nop 0
	v_pk_add_f32 v[130:131], v[132:133], v[130:131]
	s_nop 0
	v_add_f32_e32 v0, v130, v131

; __device__ __forceinline__ void load_rstd8(const float* ssq, const float* ssqc, int row0, int fq, float (&rs)[2][4]) {
;     const bool isc = row0 >= ML;
; #pragma unroll
;     for (int ai = 0; ai < 2; ++ai)
; #pragma unroll
;         for (int m = 0; m < 4; ++m) {
;             const int row = row0 + ai * HALF + m * 16;
;             float s;
;             if (!isc) { const f32x4 a = *(const f32x4*)(ssq + ((size_t)(2 * fq) * MT + row) * 4), b = *(const f32x4*)(ssq + ((size_t)(2 * fq + 1) * MT + row) * 4);
;                 s = ((a[0] + a[1]) + (a[2] + a[3])) + ((b[0] + b[1]) + (b[2] + b[3])); }
;     __device__ __forceinline__ void operator()(const f32x4 (&acc)[2][2][4][2], const Unit& u, int wr, int wc, int fr_, int fq_) const {
;         int fr = fr_, fq = fq_; asm volatile("" : "+v"(fr), "+v"(fq));
;         const int row0 = u.pm * BM + wr * 64 + fr, v = vec_of_panel(u.pm);
;         const int pn = u.pn + pn_off;
;         float rs[2][4]; load_rstd8(ssq, ssqc, row0, fq, rs);
.LBB0_405:
	v_mov_b32_e32 v240, v189
	v_mov_b32_e32 v150, v191
	s_lshl_b32 s26, s94, 8
	s_add_i32 s26, s26, s71
	v_lshrrev_b32_e32 v246, 3, v201
	v_mul_u32_u24_e32 v246, 0x22000, v246
	v_and_b32_e32 v247, 3, v201
	v_bfe_u32 v248, v201, 2, 1
	v_lshlrev_b32_e32 v247, 6, v247
	v_lshl_add_u32 v247, v248, 8, v247
	s_lshl_b32 s74, s26, 4
	v_add3_u32 v246, v246, v247, s74
	global_load_dword v247, v246, s[46:47]
	global_load_dword v248, v246, s[46:47] offset:512
	global_load_dword v249, v246, s[46:47] offset:2048
	global_load_dword v250, v246, s[46:47] offset:2560
	v_lshlrev_b32_e32 v0, 1, v150
	v_add_u32_e32 v168, s26, v240
	v_mad_i64_i32 v[146:147], s[42:43], v0, s97, 0
	v_or_b32_e32 v0, 1, v0
	v_cmp_gt_i32_e64 s[40:41], s58, v168
	v_mad_i64_i32 v[148:149], s[42:43], v0, s97, 0
	v_ashrrev_i32_e32 v169, 31, v168
	s_and_saveexec_b64 s[42:43], s[40:41]
	s_xor_b64 s[42:43], exec, s[42:43]
	s_cbranch_execz .LBB0_407
	v_lshl_add_u64 v[130:131], v[146:147], 0, v[168:169]
	v_lshl_add_u64 v[132:133], v[148:149], 0, v[168:169]
	v_lshl_add_u64 v[130:131], v[130:131], 4, s[46:47]
	v_lshl_add_u64 v[134:135], v[132:133], 4, s[46:47]
	global_load_dwordx4 v[130:133], v[130:131], off
	s_nop 0
	global_load_dwordx4 v[134:137], v[134:135], off
	s_waitcnt vmcnt(0)
	v_mov_b32_e32 v138, v130
	v_mov_b32_e32 v139, v134
	v_mov_b32_e32 v134, v131
	v_mov_b32_e32 v130, v132
	v_mov_b32_e32 v131, v136
	v_mov_b32_e32 v136, v133
	v_pk_add_f32 v[132:133], v[138:139], v[134:135]
	v_pk_add_f32 v[130:131], v[130:131], v[136:137]
	s_nop 0
	v_pk_add_f32 v[130:131], v[132:133], v[130:131]
	s_nop 0
	v_add_f32_e32 v0, v130, v131

; #define TS_MARK(word, cond) do { if (MK_TS >= 0 && (cond) && blockIdx.x == MK_TSB && wave_s == 0) { int l_; MK_LANE_ASM(l_); if (l_ == 0) { const unsigned long long t_ = __builtin_amdgcn_s_memrealtime(); MISC[16 + 2 * (word)] = (unsigned)t_; MISC[17 + 2 * (word)] = (unsigned)(t_ >> 32); } } } while (0)
; __device__ __forceinline__ void load_rstd8(const float* ssq, const float* ssqc, int row0, int fq, float (&rs)[2][4]) {
;     const bool isc = row0 >= ML;
; #pragma unroll
;     for (int ai = 0; ai < 2; ++ai)
; #pragma unroll
;         for (int m = 0; m < 4; ++m) {
;             const int row = row0 + ai * HALF + m * 16;
;             float s;
;             if (!isc) { const f32x4 a = *(const f32x4*)(ssq + ((size_t)(2 * fq) * MT + row) * 4), b = *(const f32x4*)(ssq + ((size_t)(2 * fq + 1) * MT + row) * 4);
;                 s = ((a[0] + a[1]) + (a[2] + a[3])) + ((b[0] + b[1]) + (b[2] + b[3])); }
;     __device__ __forceinline__ void operator()(const f32x4 (&acc)[2][2][4][2], const Unit& u, int wr, int wc, int fr_, int fq_) const {
;         int fr = fr_, fq = fq_; asm volatile("" : "+v"(fr), "+v"(fq));
;         const bool first_ = (MK_TS == 60 || MK_TS == 61) ? (MISC[20] == 0u) : false;
;         TS_MARK(1, MK_TS == 61 && tsl && first_); TS_MARK(0, MK_TS == 60 && tsl && first_);
;         const int row0 = u.pm * BM + wr * 64 + fr, v = vec_of_panel(u.pm);
;         float rs[2][4]; load_rstd8(ssq, ssqc, row0, fq, rs);
.LBB0_1161:
	v_mov_b32_e32 v0, v183
	v_mov_b32_e32 v130, v185
	s_lshl_b32 s38, s80, 8
	s_add_i32 s38, s38, s81
	v_lshrrev_b32_e32 v246, 3, v201
	v_mul_u32_u24_e32 v246, 0x22000, v246
	v_and_b32_e32 v247, 3, v201
	v_bfe_u32 v248, v201, 2, 1
	v_lshlrev_b32_e32 v247, 6, v247
	v_lshl_add_u32 v247, v248, 8, v247
	s_lshl_b32 s73, s38, 4
	v_add3_u32 v246, v246, v247, s73
	global_load_dword v247, v246, s[44:45]
	global_load_dword v248, v246, s[44:45] offset:512
	global_load_dword v249, v246, s[44:45] offset:2048
	global_load_dword v250, v246, s[44:45] offset:2560
	v_add_u32_e32 v166, s38, v0
	v_lshlrev_b32_e32 v0, 1, v130
	v_mad_i64_i32 v[144:145], s[62:63], v0, s97, 0
	v_or_b32_e32 v0, 1, v0
	v_cmp_gt_i32_e64 s[38:39], s58, v166
	v_mad_i64_i32 v[180:181], s[62:63], v0, s97, 0
	s_and_saveexec_b64 s[62:63], s[38:39]
	s_xor_b64 s[82:83], exec, s[62:63]
	s_cbranch_execz .LBB0_1163
	v_ashrrev_i32_e32 v167, 31, v166
	v_lshl_add_u64 v[132:133], v[144:145], 0, v[166:167]
	v_lshl_add_u64 v[134:135], v[180:181], 0, v[166:167]
	v_lshl_add_u64 v[132:133], v[132:133], 4, s[44:45]
	v_lshl_add_u64 v[136:137], v[134:135], 4, s[44:45]
	global_load_dwordx4 v[132:135], v[132:133], off
	s_nop 0
	global_load_dwordx4 v[136:139], v[136:137], off
	s_waitcnt vmcnt(0)
	v_mov_b32_e32 v140, v132
	v_mov_b32_e32 v141, v136
	v_mov_b32_e32 v136, v133
	v_mov_b32_e32 v132, v134
	v_mov_b32_e32 v133, v138
	v_mov_b32_e32 v138, v135
	v_pk_add_f32 v[134:135], v[140:141], v[136:137]
	v_pk_add_f32 v[132:133], v[132:133], v[138:139]
	s_nop 0
	v_pk_add_f32 v[132:133], v[134:135], v[132:133]
	s_nop 0
	v_add_f32_e32 v0, v132, v133
